# attention unit epilogue hand-written: combine/sub-norm/stage/gate/store split between the map-0 and map-1 wave (64 dv columns and 4 store rows each), sub_g and gate loads issued before the LDS exchang
# speedup vs baseline: 1.0056x; 1.0044x over previous
; __device__ __forceinline__ unsigned cvtpk(float lo, float hi) { f32x2 v = {lo, hi}; bf16x2_t b = __builtin_convertvector(v, bf16x2_t); return __builtin_bit_cast(unsigned, b); }
; __device__ __forceinline__ void attn_unit(unsigned char* ws, const float* sub_g, LAS unsigned char* lds, int h, int qb, float negM, float lam) {
;     ...
;     {
;         float a0 = 0.f, a1 = 0.f;
; #pragma unroll
;         for (int r = 0; r < 16; ++r) { a0 += pa[r]; a1 += pb[r]; }
;         l0 += a0; l1 += a1;
;         pw[0] = (u32x4){cvtpk(pa[0], pa[1]), cvtpk(pa[2], pa[3]), cvtpk(pa[4], pa[5]), cvtpk(pa[6], pa[7])};
;         pw[1] = (u32x4){cvtpk(pa[8], pa[9]), cvtpk(pa[10], pa[11]), cvtpk(pa[12], pa[13]), cvtpk(pa[14], pa[15])};
;         pw[2] = (u32x4){cvtpk(pb[0], pb[1]), cvtpk(pb[2], pb[3]), cvtpk(pb[4], pb[5]), cvtpk(pb[6], pb[7])};
;         pw[3] = (u32x4){cvtpk(pb[8], pb[9]), cvtpk(pb[10], pb[11]), cvtpk(pb[12], pb[13]), cvtpk(pb[14], pb[15])};
; #pragma unroll
;         for (int j = 0; j < 4; ++j)
; #pragma unroll
;             for (int b = 0; b < 4; ++b) o[b] = __builtin_amdgcn_mfma_f32_32x32x16_bf16(VFR(bV, j, b), __builtin_bit_cast(bf16x8, pw[j]), o[b], 0, 0, 0);
;     }
;     float l = l0 + l1;
;     ...
;     asm volatile("s_waitcnt vmcnt(0) lgkmcnt(0)" ::: "memory");
;     __builtin_amdgcn_s_barrier();
.Lattn_exit:
	s_waitcnt lgkmcnt(0)
	ds_read_b128 v[80:83], v249 offset:49152
	ds_read_b128 v[84:87], v249 offset:51200
	ds_read_b128 v[88:91], v249 offset:53248
	ds_read_b128 v[92:95], v249 offset:55296
	ds_read_b128 v[96:99], v249 offset:57344
	ds_read_b128 v[100:103], v249 offset:59392
	ds_read_b128 v[104:107], v249 offset:61440
	ds_read_b128 v[108:111], v249 offset:63488
	v_add_f32_e32 v222, v222, v183
	v_add_f32_e32 v223, v223, v187
	v_add_f32_e32 v222, v222, v184
	v_add_f32_e32 v223, v223, v188
	v_add_f32_e32 v222, v222, v185
	v_add_f32_e32 v223, v223, v189
	v_add_f32_e32 v222, v222, v186
	v_add_f32_e32 v223, v223, v190
	v_add_f32_e32 v222, v222, v191
	v_add_f32_e32 v223, v223, v195
	v_add_f32_e32 v222, v222, v192
	v_add_f32_e32 v223, v223, v196
	v_add_f32_e32 v222, v222, v193
	v_add_f32_e32 v223, v223, v197
	v_add_f32_e32 v222, v222, v194
	v_add_f32_e32 v223, v223, v199
	v_add_f32_e32 v222, v222, v203
	v_add_f32_e32 v223, v223, v207
	v_add_f32_e32 v222, v222, v204
	v_add_f32_e32 v223, v223, v208
	v_add_f32_e32 v222, v222, v205
	v_add_f32_e32 v223, v223, v209
	v_add_f32_e32 v222, v222, v206
	v_add_f32_e32 v223, v223, v210
	v_add_f32_e32 v222, v222, v211
	v_add_f32_e32 v223, v223, v216
	v_add_f32_e32 v222, v222, v213
	v_add_f32_e32 v223, v223, v217
	v_add_f32_e32 v222, v222, v214
	v_add_f32_e32 v223, v223, v218
	v_add_f32_e32 v222, v222, v215
	v_add_f32_e32 v223, v223, v219
	v_cvt_pk_bf16_f32 v232, v183, v184
	v_cvt_pk_bf16_f32 v233, v185, v186
	v_cvt_pk_bf16_f32 v234, v191, v192
	v_cvt_pk_bf16_f32 v235, v193, v194
	v_cvt_pk_bf16_f32 v236, v187, v188
	v_cvt_pk_bf16_f32 v237, v189, v190
	v_cvt_pk_bf16_f32 v238, v195, v196
	v_cvt_pk_bf16_f32 v239, v197, v199
	v_cvt_pk_bf16_f32 v228, v203, v204
	v_cvt_pk_bf16_f32 v229, v205, v206
	v_cvt_pk_bf16_f32 v230, v211, v213
	v_cvt_pk_bf16_f32 v231, v214, v215
	v_cvt_pk_bf16_f32 v240, v207, v208
	v_cvt_pk_bf16_f32 v241, v209, v210
	v_cvt_pk_bf16_f32 v242, v216, v217
	v_cvt_pk_bf16_f32 v243, v218, v219
	s_lshl_b32 s8, s29, 14
	s_add_i32 s29, s8, 0
	s_waitcnt lgkmcnt(7)
	v_mfma_f32_16x16x32_bf16 v[64:67], v[80:83], v[232:235], v[64:67]
	v_mfma_f32_16x16x32_bf16 v[68:71], v[80:83], v[236:239], v[68:71]
	s_waitcnt lgkmcnt(6)
	v_mfma_f32_16x16x32_bf16 v[72:75], v[84:87], v[232:235], v[72:75]
	v_mfma_f32_16x16x32_bf16 v[76:79], v[84:87], v[236:239], v[76:79]
	s_waitcnt lgkmcnt(5)
	v_mfma_f32_16x16x32_bf16 v[48:51], v[88:91], v[232:235], v[48:51]
	v_mfma_f32_16x16x32_bf16 v[52:55], v[88:91], v[236:239], v[52:55]
	s_waitcnt lgkmcnt(4)
	v_mfma_f32_16x16x32_bf16 v[56:59], v[92:95], v[232:235], v[56:59]
	v_mfma_f32_16x16x32_bf16 v[60:63], v[92:95], v[236:239], v[60:63]
	s_waitcnt lgkmcnt(3)
	v_mfma_f32_16x16x32_bf16 v[32:35], v[96:99], v[232:235], v[32:35]
	v_mfma_f32_16x16x32_bf16 v[36:39], v[96:99], v[236:239], v[36:39]
	s_waitcnt lgkmcnt(2)
	v_mfma_f32_16x16x32_bf16 v[40:43], v[100:103], v[232:235], v[40:43]
	v_mfma_f32_16x16x32_bf16 v[44:47], v[100:103], v[236:239], v[44:47]
	s_waitcnt lgkmcnt(1)
	v_mfma_f32_16x16x32_bf16 v[16:19], v[104:107], v[232:235], v[16:19]
	v_mfma_f32_16x16x32_bf16 v[20:23], v[104:107], v[236:239], v[20:23]
	s_waitcnt lgkmcnt(0)
	v_mfma_f32_16x16x32_bf16 v[24:27], v[108:111], v[232:235], v[24:27]
	v_mfma_f32_16x16x32_bf16 v[28:31], v[108:111], v[236:239], v[28:31]
	ds_read_b128 v[4:7], v250 offset:49152
	ds_read_b128 v[8:11], v250 offset:51200
	ds_read_b128 v[12:15], v250 offset:53248
	ds_read_b128 v[224:227], v250 offset:55296
	ds_read_b128 v[112:115], v250 offset:57344
	ds_read_b128 v[116:119], v250 offset:59392
	ds_read_b128 v[120:123], v250 offset:61440
	ds_read_b128 v[124:127], v250 offset:63488
	s_waitcnt lgkmcnt(7)
	v_mfma_f32_16x16x32_bf16 v[64:67], v[4:7], v[228:231], v[64:67]
	v_mfma_f32_16x16x32_bf16 v[68:71], v[4:7], v[240:243], v[68:71]
	s_waitcnt lgkmcnt(6)
	v_mfma_f32_16x16x32_bf16 v[72:75], v[8:11], v[228:231], v[72:75]
	v_mfma_f32_16x16x32_bf16 v[76:79], v[8:11], v[240:243], v[76:79]
	s_waitcnt lgkmcnt(5)
	v_mfma_f32_16x16x32_bf16 v[48:51], v[12:15], v[228:231], v[48:51]
	v_mfma_f32_16x16x32_bf16 v[52:55], v[12:15], v[240:243], v[52:55]
	s_waitcnt lgkmcnt(4)
	v_mfma_f32_16x16x32_bf16 v[56:59], v[224:227], v[228:231], v[56:59]
	v_mfma_f32_16x16x32_bf16 v[60:63], v[224:227], v[240:243], v[60:63]
	s_waitcnt lgkmcnt(3)
	v_mfma_f32_16x16x32_bf16 v[32:35], v[112:115], v[228:231], v[32:35]
	v_mfma_f32_16x16x32_bf16 v[36:39], v[112:115], v[240:243], v[36:39]
	s_waitcnt lgkmcnt(2)
	v_mfma_f32_16x16x32_bf16 v[40:43], v[116:119], v[228:231], v[40:43]
	v_mfma_f32_16x16x32_bf16 v[44:47], v[116:119], v[240:243], v[44:47]
	s_waitcnt lgkmcnt(1)
	v_mfma_f32_16x16x32_bf16 v[16:19], v[120:123], v[228:231], v[16:19]
	v_mfma_f32_16x16x32_bf16 v[20:23], v[120:123], v[240:243], v[20:23]
	s_waitcnt lgkmcnt(0)
	v_mfma_f32_16x16x32_bf16 v[24:27], v[124:127], v[228:231], v[24:27]
	v_mfma_f32_16x16x32_bf16 v[28:31], v[124:127], v[240:243], v[28:31]
	s_waitcnt vmcnt(0)
	s_barrier
; #define LAS __attribute__((address_space(3)))
; __device__ __forceinline__ unsigned cvtpk(float lo, float hi) { f32x2 v = {lo, hi}; bf16x2_t b = __builtin_convertvector(v, bf16x2_t); return __builtin_bit_cast(unsigned, b); }
; __device__ __forceinline__ void attn_unit(unsigned char* ws, const float* sub_g, LAS unsigned char* lds, int h, int qb, float negM, float lam) {
;     ...
;     l += __shfl_xor(l, 32);
;     const float inv = 1.0f / l;
;     LAS float* xw = (LAS float*)(lds + AT_XOFF + wq * 16384);
;     if (map == 1) {
;         const float f = inv * lam;
; #pragma unroll
;         for (int b = 0; b < 4; ++b)
; #pragma unroll
;             for (int r = 0; r < 16; ++r) xw[(b * 16 + r) * 64 + lane] = o[b][r] * f;
;     }
;     __syncthreads();
;     ...
;                 const f32x4 sg = *(const f32x4*)(sub_g + dv);
;                 u32x2 w; w.x = cvtpk(o[b][4 * r4 + 0] * rs * sg[0], o[b][4 * r4 + 1] * rs * sg[1]); w.y = cvtpk(o[b][4 * r4 + 2] * rs * sg[2], o[b][4 * r4 + 3] * rs * sg[3]);
;                 *(LAS u32x2*)(stg + r32 * 272 + dv * 2) = w;
;             }
;         asm volatile("s_waitcnt lgkmcnt(0)" ::: "memory");
;         const bf16_t* GA = (const bf16_t*)(ws + WS_GA); bf16_t* MIX = (bf16_t*)(ws + WS_MIX);
;         u32x4 gvs[8];
; #pragma unroll
;         for (int i = 0; i < 8; ++i) gvs[i] = *(const u32x4*)(GA + (size_t)(qrow0 + (lane >> 4) + 4 * i) * 1024 + h * 128 + (lane & 15) * 8);
	v_mov_b32_e32 v251, v222
	v_mov_b32_e32 v252, v223
	s_nop 1
	v_permlane16_swap_b32_e32 v251, v222
	v_permlane16_swap_b32_e32 v252, v223
	v_add_f32_e32 v222, v222, v251
	v_add_f32_e32 v223, v223, v252
	v_mov_b32_e32 v251, v222
	v_mov_b32_e32 v252, v223
	s_nop 1
	v_permlane32_swap_b32_e32 v251, v222
	v_permlane32_swap_b32_e32 v252, v223
	v_add_f32_e32 v222, v222, v251
	v_add_f32_e32 v223, v223, v252
	v_and_b32_e32 v251, 16, v220
	v_cmp_ne_u32_e32 vcc, 0, v251
	v_cndmask_b32_e32 v88, v222, v223, vcc
	s_nop 7
	v_permlane16_swap_b32_e32 v64, v68
	v_permlane16_swap_b32_e32 v65, v69
	v_permlane16_swap_b32_e32 v66, v70
	v_permlane16_swap_b32_e32 v67, v71
	v_permlane16_swap_b32_e32 v72, v76
	v_permlane16_swap_b32_e32 v73, v77
	v_permlane16_swap_b32_e32 v74, v78
	v_permlane16_swap_b32_e32 v75, v79
	v_permlane16_swap_b32_e32 v48, v52
	v_permlane16_swap_b32_e32 v49, v53
	v_permlane16_swap_b32_e32 v50, v54
	v_permlane16_swap_b32_e32 v51, v55
	v_permlane16_swap_b32_e32 v56, v60
	v_permlane16_swap_b32_e32 v57, v61
	v_permlane16_swap_b32_e32 v58, v62
	v_permlane16_swap_b32_e32 v59, v63
	v_permlane16_swap_b32_e32 v32, v36
	v_permlane16_swap_b32_e32 v33, v37
	v_permlane16_swap_b32_e32 v34, v38
	v_permlane16_swap_b32_e32 v35, v39
	v_permlane16_swap_b32_e32 v40, v44
	v_permlane16_swap_b32_e32 v41, v45
	v_permlane16_swap_b32_e32 v42, v46
	v_permlane16_swap_b32_e32 v43, v47
	v_permlane16_swap_b32_e32 v16, v20
	v_permlane16_swap_b32_e32 v17, v21
	v_permlane16_swap_b32_e32 v18, v22
	v_permlane16_swap_b32_e32 v19, v23
	v_permlane16_swap_b32_e32 v24, v28
	v_permlane16_swap_b32_e32 v25, v29
	v_permlane16_swap_b32_e32 v26, v30
	v_permlane16_swap_b32_e32 v27, v31
	v_permlane32_swap_b32_e32 v64, v68
	v_permlane32_swap_b32_e32 v65, v69
	v_permlane32_swap_b32_e32 v66, v70
	v_permlane32_swap_b32_e32 v67, v71
	v_permlane32_swap_b32_e32 v72, v76
	v_permlane32_swap_b32_e32 v73, v77
	v_permlane32_swap_b32_e32 v74, v78
	v_permlane32_swap_b32_e32 v75, v79
	v_permlane32_swap_b32_e32 v48, v52
	v_permlane32_swap_b32_e32 v49, v53
	v_permlane32_swap_b32_e32 v50, v54
	v_permlane32_swap_b32_e32 v51, v55
	v_permlane32_swap_b32_e32 v56, v60
	v_permlane32_swap_b32_e32 v57, v61
	v_permlane32_swap_b32_e32 v58, v62
	v_permlane32_swap_b32_e32 v59, v63
	v_permlane32_swap_b32_e32 v32, v36
	v_permlane32_swap_b32_e32 v33, v37
	v_permlane32_swap_b32_e32 v34, v38
	v_permlane32_swap_b32_e32 v35, v39
	v_permlane32_swap_b32_e32 v40, v44
	v_permlane32_swap_b32_e32 v41, v45
	v_permlane32_swap_b32_e32 v42, v46
	v_permlane32_swap_b32_e32 v43, v47
	v_permlane32_swap_b32_e32 v16, v20
	v_permlane32_swap_b32_e32 v17, v21
	v_permlane32_swap_b32_e32 v18, v22
	v_permlane32_swap_b32_e32 v19, v23
	v_permlane32_swap_b32_e32 v24, v28
	v_permlane32_swap_b32_e32 v25, v29
	v_permlane32_swap_b32_e32 v26, v30
	v_permlane32_swap_b32_e32 v27, v31
	v_div_scale_f32 v89, s[30:31], v88, v88, 1.0
	v_rcp_f32_e32 v90, v89
	s_nop 1
	v_fma_f32 v80, -v89, v90, 1.0
	v_fmac_f32_e32 v90, v80, v90
	v_div_scale_f32 v80, vcc, 1.0, v88, 1.0
	v_mul_f32_e32 v81, v80, v90
	v_fma_f32 v82, -v89, v81, v80
	v_fmac_f32_e32 v81, v82, v90
	s_nop 1
	v_fma_f32 v80, -v89, v81, v80
	s_nop 1
	v_div_fmas_f32 v80, v80, v90, v81
	v_div_fixup_f32 v90, v80, v88, 1.0
	v_lshl_add_u32 v80, v221, 2, s29
	s_cmp_eq_u32 s28, 1
	s_cbranch_scc1 .Lepi_m1
.Lepi_m0:
	s_add_i32 s37, s21, 0
	v_add_u32_e32 v82, s37, v150
	v_mov_b32_e32 v83, 0
	s_lshl_b32 s30, s24, 1
	s_mov_b32 s31, 0
	s_mov_b64 s[34:35], 0x2000
	s_mov_b64 s[38:39], 0x4000
	global_load_dwordx4 v[184:187], v[132:133], off
	global_load_dwordx4 v[188:191], v[132:133], off offset:32
	global_load_dwordx4 v[192:195], v[132:133], off offset:64
	global_load_dwordx4 v[196:199], v[132:133], off offset:96
	global_load_dwordx4 v[200:203], v[132:133], off offset:128
	global_load_dwordx4 v[204:207], v[132:133], off offset:160
	global_load_dwordx4 v[208:211], v[132:133], off offset:192
	global_load_dwordx4 v[212:215], v[132:133], off offset:224
	v_lshlrev_b64 v[92:93], 11, v[82:83]
	v_lshlrev_b64 v[94:95], 12, v[82:83]
	v_lshl_add_u64 v[92:93], v[92:93], 0, s[30:31]
	v_lshl_add_u64 v[94:95], v[94:95], 0, s[30:31]
	v_lshl_add_u64 v[140:141], v[134:135], 0, v[92:93]
	v_lshl_add_u64 v[240:241], v[138:139], 0, v[94:95]
	v_lshl_add_u64 v[142:143], v[140:141], 0, s[34:35]
	v_lshl_add_u64 v[242:243], v[240:241], 0, s[38:39]
	v_lshl_add_u64 v[144:145], v[142:143], 0, s[34:35]
	v_lshl_add_u64 v[244:245], v[242:243], 0, s[38:39]
	v_lshl_add_u64 v[146:147], v[144:145], 0, s[34:35]
	v_lshl_add_u64 v[222:223], v[244:245], 0, s[38:39]
	global_load_dwordx4 v[224:227], v[140:141], off
	global_load_dwordx4 v[228:231], v[142:143], off
	global_load_dwordx4 v[232:235], v[144:145], off
	global_load_dwordx4 v[236:239], v[146:147], off
	v_mov_b32_e32 v91, v90
	v_mul_f32_e32 v92, v32, v91
	v_mul_f32_e32 v93, v33, v91
	ds_write2st64_b32 v80, v92, v93 offset0:0 offset1:1
	v_mul_f32_e32 v94, v34, v91
	v_mul_f32_e32 v95, v35, v91
	ds_write2st64_b32 v80, v94, v95 offset0:2 offset1:3
	v_mul_f32_e32 v92, v36, v91
	v_mul_f32_e32 v93, v37, v91
	ds_write2st64_b32 v80, v92, v93 offset0:4 offset1:5
	v_mul_f32_e32 v94, v38, v91
	v_mul_f32_e32 v95, v39, v91
	ds_write2st64_b32 v80, v94, v95 offset0:6 offset1:7
	v_mul_f32_e32 v92, v40, v91
	v_mul_f32_e32 v93, v41, v91
	ds_write2st64_b32 v80, v92, v93 offset0:8 offset1:9
	v_mul_f32_e32 v94, v42, v91
	v_mul_f32_e32 v95, v43, v91
	ds_write2st64_b32 v80, v94, v95 offset0:10 offset1:11
	v_mul_f32_e32 v92, v44, v91
	v_mul_f32_e32 v93, v45, v91
	ds_write2st64_b32 v80, v92, v93 offset0:12 offset1:13
	v_mul_f32_e32 v94, v46, v91
	v_mul_f32_e32 v95, v47, v91
	ds_write2st64_b32 v80, v94, v95 offset0:14 offset1:15
	v_mul_f32_e32 v92, v16, v91
	v_mul_f32_e32 v93, v17, v91
	ds_write2st64_b32 v80, v92, v93 offset0:16 offset1:17
	v_mul_f32_e32 v94, v18, v91
	v_mul_f32_e32 v95, v19, v91
	ds_write2st64_b32 v80, v94, v95 offset0:18 offset1:19
	v_mul_f32_e32 v92, v20, v91
	v_mul_f32_e32 v93, v21, v91
	ds_write2st64_b32 v80, v92, v93 offset0:20 offset1:21
	v_mul_f32_e32 v94, v22, v91
	v_mul_f32_e32 v95, v23, v91
	ds_write2st64_b32 v80, v94, v95 offset0:22 offset1:23
	v_mul_f32_e32 v92, v24, v91
	v_mul_f32_e32 v93, v25, v91
	ds_write2st64_b32 v80, v92, v93 offset0:24 offset1:25
	v_mul_f32_e32 v94, v26, v91
	v_mul_f32_e32 v95, v27, v91
	ds_write2st64_b32 v80, v94, v95 offset0:26 offset1:27
	v_mul_f32_e32 v92, v28, v91
	v_mul_f32_e32 v93, v29, v91
	ds_write2st64_b32 v80, v92, v93 offset0:28 offset1:29
	v_mul_f32_e32 v94, v30, v91
	v_mul_f32_e32 v95, v31, v91
	ds_write2st64_b32 v80, v94, v95 offset0:30 offset1:31
	v_lshl_add_u32 v81, v149, 3, v155
	v_add_u32_e32 v81, s29, v81
	v_lshl_add_u32 v84, v153, 4, v137
	v_add_u32_e32 v84, s29, v84
	s_lshr_b32 s36, s29, 5
	s_add_i32 s36, s36, 0x20000
	v_lshl_add_u32 v85, v148, 2, s36
	s_waitcnt lgkmcnt(0)
	s_barrier
; #define LAS __attribute__((address_space(3)))
; __device__ __forceinline__ unsigned cvtpk(float lo, float hi) { f32x2 v = {lo, hi}; bf16x2_t b = __builtin_convertvector(v, bf16x2_t); return __builtin_bit_cast(unsigned, b); }
; __device__ __forceinline__ void attn_unit(unsigned char* ws, const float* sub_g, LAS unsigned char* lds, int h, int qb, float negM, float lam) {
;     ...
;     if (map == 0) {
;         float ss = 0.f;
; #pragma unroll
;         for (int b = 0; b < 4; ++b)
; #pragma unroll
;             for (int r = 0; r < 16; ++r) { const float v = o[b][r] * inv - xw[(b * 16 + r) * 64 + lane]; o[b][r] = v; ss += v * v; }
;         ss += __shfl_xor(ss, 32);
;         const float rs = __builtin_amdgcn_rsqf(ss * (1.0f / VD) + EPS) * (1.0f - LAM_INIT);
;         LAS unsigned char* stg = (LAS unsigned char*)xw;
; #pragma unroll
;         for (int b = 0; b < 4; ++b)
; #pragma unroll
;             for (int r4 = 0; r4 < 4; ++r4) {
;                 const int dv = 32 * b + 8 * r4 + 4 * hi;
;                 const f32x4 sg = *(const f32x4*)(sub_g + dv);
;                 u32x2 w; w.x = cvtpk(o[b][4 * r4 + 0] * rs * sg[0], o[b][4 * r4 + 1] * rs * sg[1]); w.y = cvtpk(o[b][4 * r4 + 2] * rs * sg[2], o[b][4 * r4 + 3] * rs * sg[3]);
;                 *(LAS u32x2*)(stg + r32 * 272 + dv * 2) = w;
;             }
;         asm volatile("s_waitcnt lgkmcnt(0)" ::: "memory");
	ds_read2st64_b32 v[96:97], v80 offset0:32 offset1:33
	ds_read2st64_b32 v[98:99], v80 offset0:34 offset1:35
	ds_read2st64_b32 v[100:101], v80 offset0:36 offset1:37
	ds_read2st64_b32 v[102:103], v80 offset0:38 offset1:39
	ds_read2st64_b32 v[104:105], v80 offset0:40 offset1:41
	ds_read2st64_b32 v[106:107], v80 offset0:42 offset1:43
	ds_read2st64_b32 v[108:109], v80 offset0:44 offset1:45
	ds_read2st64_b32 v[110:111], v80 offset0:46 offset1:47
	s_waitcnt lgkmcnt(7)
	v_fma_f32 v64, v64, v91, -v96
	v_mul_f32_e32 v86, v64, v64
	v_fma_f32 v65, v65, v91, -v97
	v_mul_f32_e32 v87, v65, v65
	s_waitcnt lgkmcnt(6)
	v_fma_f32 v66, v66, v91, -v98
	v_fmac_f32_e32 v86, v66, v66
	v_fma_f32 v67, v67, v91, -v99
	v_fmac_f32_e32 v87, v67, v67
	s_waitcnt lgkmcnt(5)
	v_fma_f32 v68, v68, v91, -v100
	v_fmac_f32_e32 v86, v68, v68
	v_fma_f32 v69, v69, v91, -v101
	v_fmac_f32_e32 v87, v69, v69
	s_waitcnt lgkmcnt(4)
	v_fma_f32 v70, v70, v91, -v102
	v_fmac_f32_e32 v86, v70, v70
	v_fma_f32 v71, v71, v91, -v103
	v_fmac_f32_e32 v87, v71, v71
	ds_read2st64_b32 v[112:113], v80 offset0:48 offset1:49
	ds_read2st64_b32 v[114:115], v80 offset0:50 offset1:51
	ds_read2st64_b32 v[116:117], v80 offset0:52 offset1:53
	ds_read2st64_b32 v[118:119], v80 offset0:54 offset1:55
	ds_read2st64_b32 v[120:121], v80 offset0:56 offset1:57
	ds_read2st64_b32 v[122:123], v80 offset0:58 offset1:59
	ds_read2st64_b32 v[124:125], v80 offset0:60 offset1:61
	ds_read2st64_b32 v[126:127], v80 offset0:62 offset1:63
	s_waitcnt lgkmcnt(11)
	v_fma_f32 v72, v72, v91, -v104
	v_fmac_f32_e32 v86, v72, v72
	v_fma_f32 v73, v73, v91, -v105
	v_fmac_f32_e32 v87, v73, v73
	s_waitcnt lgkmcnt(10)
	v_fma_f32 v74, v74, v91, -v106
	v_fmac_f32_e32 v86, v74, v74
	v_fma_f32 v75, v75, v91, -v107
	v_fmac_f32_e32 v87, v75, v75
	s_waitcnt lgkmcnt(9)
	v_fma_f32 v76, v76, v91, -v108
	v_fmac_f32_e32 v86, v76, v76
	v_fma_f32 v77, v77, v91, -v109
	v_fmac_f32_e32 v87, v77, v77
	s_waitcnt lgkmcnt(8)
	v_fma_f32 v78, v78, v91, -v110
	v_fmac_f32_e32 v86, v78, v78
	v_fma_f32 v79, v79, v91, -v111
	v_fmac_f32_e32 v87, v79, v79
	s_waitcnt lgkmcnt(7)
	v_fma_f32 v48, v48, v91, -v112
	v_fmac_f32_e32 v86, v48, v48
	v_fma_f32 v49, v49, v91, -v113
	v_fmac_f32_e32 v87, v49, v49
	s_waitcnt lgkmcnt(6)
	v_fma_f32 v50, v50, v91, -v114
	v_fmac_f32_e32 v86, v50, v50
	v_fma_f32 v51, v51, v91, -v115
	v_fmac_f32_e32 v87, v51, v51
	s_waitcnt lgkmcnt(5)
	v_fma_f32 v52, v52, v91, -v116
	v_fmac_f32_e32 v86, v52, v52
	v_fma_f32 v53, v53, v91, -v117
	v_fmac_f32_e32 v87, v53, v53
	s_waitcnt lgkmcnt(4)
	v_fma_f32 v54, v54, v91, -v118
	v_fmac_f32_e32 v86, v54, v54
	v_fma_f32 v55, v55, v91, -v119
	v_fmac_f32_e32 v87, v55, v55
	s_waitcnt lgkmcnt(3)
	v_fma_f32 v56, v56, v91, -v120
	v_fmac_f32_e32 v86, v56, v56
	v_fma_f32 v57, v57, v91, -v121
	v_fmac_f32_e32 v87, v57, v57
	s_waitcnt lgkmcnt(2)
	v_fma_f32 v58, v58, v91, -v122
	v_fmac_f32_e32 v86, v58, v58
	v_fma_f32 v59, v59, v91, -v123
	v_fmac_f32_e32 v87, v59, v59
	s_waitcnt lgkmcnt(1)
	v_fma_f32 v60, v60, v91, -v124
	v_fmac_f32_e32 v86, v60, v60
	v_fma_f32 v61, v61, v91, -v125
	v_fmac_f32_e32 v87, v61, v61
	s_waitcnt lgkmcnt(0)
	v_fma_f32 v62, v62, v91, -v126
	v_fmac_f32_e32 v86, v62, v62
	v_fma_f32 v63, v63, v91, -v127
	v_fmac_f32_e32 v87, v63, v63
	v_add_f32_e32 v86, v86, v87
	v_mov_b32_e32 v92, v86
	s_nop 1
	v_permlane32_swap_b32_e32 v92, v86
	v_add_f32_e32 v86, v86, v92
	ds_write_b32 v85, v86
	s_waitcnt lgkmcnt(0)
	s_barrier
	ds_read_b32 v92, v85 offset:256
	s_waitcnt lgkmcnt(0)
	v_add_f32_e32 v86, v86, v92
	v_fmamk_f32 v86, v86, 0x3c000000, v182
	v_rsq_f32_e32 v86, v86
	s_nop 0
	v_mul_f32_e32 v86, 0x3f4ccccd, v86
	s_waitcnt vmcnt(4)
	v_mul_f32_e32 v64, v64, v86
	v_mul_f32_e32 v65, v65, v86
	v_mul_f32_e32 v66, v66, v86
	v_mul_f32_e32 v67, v67, v86
	v_mul_f32_e32 v64, v64, v184
	v_mul_f32_e32 v65, v65, v185
	v_mul_f32_e32 v66, v66, v186
	v_mul_f32_e32 v67, v67, v187
	v_cvt_pk_bf16_f32 v92, v64, v65
	v_cvt_pk_bf16_f32 v93, v66, v67
	ds_write_b64 v81, v[92:93] offset:0
	v_mul_f32_e32 v68, v68, v86
	v_mul_f32_e32 v69, v69, v86
	v_mul_f32_e32 v70, v70, v86
	v_mul_f32_e32 v71, v71, v86
	v_mul_f32_e32 v68, v68, v188
	v_mul_f32_e32 v69, v69, v189
	v_mul_f32_e32 v70, v70, v190
	v_mul_f32_e32 v71, v71, v191
	v_cvt_pk_bf16_f32 v94, v68, v69
	v_cvt_pk_bf16_f32 v95, v70, v71
	ds_write_b64 v81, v[94:95] offset:16
	v_mul_f32_e32 v72, v72, v86
	v_mul_f32_e32 v73, v73, v86
	v_mul_f32_e32 v74, v74, v86
	v_mul_f32_e32 v75, v75, v86
	v_mul_f32_e32 v72, v72, v192
	v_mul_f32_e32 v73, v73, v193
	v_mul_f32_e32 v74, v74, v194
	v_mul_f32_e32 v75, v75, v195
	v_cvt_pk_bf16_f32 v92, v72, v73
	v_cvt_pk_bf16_f32 v93, v74, v75
	ds_write_b64 v81, v[92:93] offset:32
	v_mul_f32_e32 v76, v76, v86
	v_mul_f32_e32 v77, v77, v86
	v_mul_f32_e32 v78, v78, v86
	v_mul_f32_e32 v79, v79, v86
	v_mul_f32_e32 v76, v76, v196
	v_mul_f32_e32 v77, v77, v197
	v_mul_f32_e32 v78, v78, v198
	v_mul_f32_e32 v79, v79, v199
	v_cvt_pk_bf16_f32 v94, v76, v77
	v_cvt_pk_bf16_f32 v95, v78, v79
	ds_write_b64 v81, v[94:95] offset:48
	v_mul_f32_e32 v48, v48, v86
	v_mul_f32_e32 v49, v49, v86
	v_mul_f32_e32 v50, v50, v86
	v_mul_f32_e32 v51, v51, v86
	v_mul_f32_e32 v48, v48, v200
	v_mul_f32_e32 v49, v49, v201
	v_mul_f32_e32 v50, v50, v202
	v_mul_f32_e32 v51, v51, v203
	v_cvt_pk_bf16_f32 v92, v48, v49
	v_cvt_pk_bf16_f32 v93, v50, v51
	ds_write_b64 v81, v[92:93] offset:64
	v_mul_f32_e32 v52, v52, v86
	v_mul_f32_e32 v53, v53, v86
	v_mul_f32_e32 v54, v54, v86
	v_mul_f32_e32 v55, v55, v86
	v_mul_f32_e32 v52, v52, v204
	v_mul_f32_e32 v53, v53, v205
	v_mul_f32_e32 v54, v54, v206
	v_mul_f32_e32 v55, v55, v207
	v_cvt_pk_bf16_f32 v94, v52, v53
	v_cvt_pk_bf16_f32 v95, v54, v55
	ds_write_b64 v81, v[94:95] offset:80
	v_mul_f32_e32 v56, v56, v86
	v_mul_f32_e32 v57, v57, v86
	v_mul_f32_e32 v58, v58, v86
	v_mul_f32_e32 v59, v59, v86
	v_mul_f32_e32 v56, v56, v208
	v_mul_f32_e32 v57, v57, v209
	v_mul_f32_e32 v58, v58, v210
	v_mul_f32_e32 v59, v59, v211
	v_cvt_pk_bf16_f32 v92, v56, v57
	v_cvt_pk_bf16_f32 v93, v58, v59
	ds_write_b64 v81, v[92:93] offset:96
	v_mul_f32_e32 v60, v60, v86
	v_mul_f32_e32 v61, v61, v86
	v_mul_f32_e32 v62, v62, v86
	v_mul_f32_e32 v63, v63, v86
	v_mul_f32_e32 v60, v60, v212
	v_mul_f32_e32 v61, v61, v213
	v_mul_f32_e32 v62, v62, v214
	v_mul_f32_e32 v63, v63, v215
	v_cvt_pk_bf16_f32 v94, v60, v61
	v_cvt_pk_bf16_f32 v95, v62, v63
	ds_write_b64 v81, v[94:95] offset:112
	s_waitcnt lgkmcnt(0)
	s_barrier
; #define LAS __attribute__((address_space(3)))
; __device__ __forceinline__ unsigned cvtpk(float lo, float hi) { f32x2 v = {lo, hi}; bf16x2_t b = __builtin_convertvector(v, bf16x2_t); return __builtin_bit_cast(unsigned, b); }
; __device__ __forceinline__ void attn_unit(unsigned char* ws, const float* sub_g, LAS unsigned char* lds, int h, int qb, float negM, float lam) {
;     ...
;         const bf16_t* GA = (const bf16_t*)(ws + WS_GA); bf16_t* MIX = (bf16_t*)(ws + WS_MIX);
;         u32x4 gvs[8];
; #pragma unroll
;         for (int i = 0; i < 8; ++i) gvs[i] = *(const u32x4*)(GA + (size_t)(qrow0 + (lane >> 4) + 4 * i) * 1024 + h * 128 + (lane & 15) * 8);
; #pragma unroll
;         for (int i = 0; i < 8; ++i) {
;             const int q = (lane >> 4) + 4 * i, ch = lane & 15;
;             const u32x4 ov = *(const LAS u32x4*)(stg + q * 272 + ch * 16);
;             const size_t tok = (size_t)(qrow0 + q);
;             const u32x4 gv = gvs[i];
;             u32x4 w;
;             w.x = cvtpk(bf_lo(ov.x) * bf_lo(gv.x), bf_hi(ov.x) * bf_hi(gv.x)); w.y = cvtpk(bf_lo(ov.y) * bf_lo(gv.y), bf_hi(ov.y) * bf_hi(gv.y));
;             w.z = cvtpk(bf_lo(ov.z) * bf_lo(gv.z), bf_hi(ov.z) * bf_hi(gv.z)); w.w = cvtpk(bf_lo(ov.w) * bf_lo(gv.w), bf_hi(ov.w) * bf_hi(gv.w));
;             *(u32x4*)(MIX + tok * DM + h * 128 + ch * 8) = w;
;         }
	ds_read_b128 v[96:99], v84 offset:0
	ds_read_b128 v[100:103], v84 offset:1088
	ds_read_b128 v[104:107], v84 offset:2176
	ds_read_b128 v[108:111], v84 offset:3264
	s_waitcnt vmcnt(0)
	s_waitcnt lgkmcnt(3)
	v_lshlrev_b32_e32 v92, 16, v96
	v_and_b32_e32 v93, 0xffff0000, v96
	v_lshlrev_b32_e32 v94, 16, v224
	v_and_b32_e32 v95, 0xffff0000, v224
	v_mul_f32_e32 v92, v92, v94
	v_mul_f32_e32 v93, v93, v95
	v_cvt_pk_bf16_f32 v112, v92, v93
	v_lshlrev_b32_e32 v92, 16, v97
	v_and_b32_e32 v93, 0xffff0000, v97
	v_lshlrev_b32_e32 v94, 16, v225
	v_and_b32_e32 v95, 0xffff0000, v225
	v_mul_f32_e32 v92, v92, v94
	v_mul_f32_e32 v93, v93, v95
	v_cvt_pk_bf16_f32 v113, v92, v93
	v_lshlrev_b32_e32 v92, 16, v98
	v_and_b32_e32 v93, 0xffff0000, v98
	v_lshlrev_b32_e32 v94, 16, v226
	v_and_b32_e32 v95, 0xffff0000, v226
	v_mul_f32_e32 v92, v92, v94
	v_mul_f32_e32 v93, v93, v95
	v_cvt_pk_bf16_f32 v114, v92, v93
	v_lshlrev_b32_e32 v92, 16, v99
	v_and_b32_e32 v93, 0xffff0000, v99
	v_lshlrev_b32_e32 v94, 16, v227
	v_and_b32_e32 v95, 0xffff0000, v227
	v_mul_f32_e32 v92, v92, v94
	v_mul_f32_e32 v93, v93, v95
	v_cvt_pk_bf16_f32 v115, v92, v93
	global_store_dwordx4 v[240:241], v[112:115], off
	s_waitcnt lgkmcnt(2)
	v_lshlrev_b32_e32 v92, 16, v100
	v_and_b32_e32 v93, 0xffff0000, v100
	v_lshlrev_b32_e32 v94, 16, v228
	v_and_b32_e32 v95, 0xffff0000, v228
	v_mul_f32_e32 v92, v92, v94
	v_mul_f32_e32 v93, v93, v95
	v_cvt_pk_bf16_f32 v116, v92, v93
	v_lshlrev_b32_e32 v92, 16, v101
	v_and_b32_e32 v93, 0xffff0000, v101
	v_lshlrev_b32_e32 v94, 16, v229
	v_and_b32_e32 v95, 0xffff0000, v229
	v_mul_f32_e32 v92, v92, v94
	v_mul_f32_e32 v93, v93, v95
	v_cvt_pk_bf16_f32 v117, v92, v93
	v_lshlrev_b32_e32 v92, 16, v102
	v_and_b32_e32 v93, 0xffff0000, v102
	v_lshlrev_b32_e32 v94, 16, v230
	v_and_b32_e32 v95, 0xffff0000, v230
	v_mul_f32_e32 v92, v92, v94
	v_mul_f32_e32 v93, v93, v95
	v_cvt_pk_bf16_f32 v118, v92, v93
	v_lshlrev_b32_e32 v92, 16, v103
	v_and_b32_e32 v93, 0xffff0000, v103
	v_lshlrev_b32_e32 v94, 16, v231
	v_and_b32_e32 v95, 0xffff0000, v231
	v_mul_f32_e32 v92, v92, v94
	v_mul_f32_e32 v93, v93, v95
	v_cvt_pk_bf16_f32 v119, v92, v93
	global_store_dwordx4 v[242:243], v[116:119], off
	s_waitcnt lgkmcnt(1)
	v_lshlrev_b32_e32 v92, 16, v104
	v_and_b32_e32 v93, 0xffff0000, v104
	v_lshlrev_b32_e32 v94, 16, v232
	v_and_b32_e32 v95, 0xffff0000, v232
	v_mul_f32_e32 v92, v92, v94
	v_mul_f32_e32 v93, v93, v95
	v_cvt_pk_bf16_f32 v120, v92, v93
	v_lshlrev_b32_e32 v92, 16, v105
	v_and_b32_e32 v93, 0xffff0000, v105
	v_lshlrev_b32_e32 v94, 16, v233
	v_and_b32_e32 v95, 0xffff0000, v233
	v_mul_f32_e32 v92, v92, v94
	v_mul_f32_e32 v93, v93, v95
	v_cvt_pk_bf16_f32 v121, v92, v93
	v_lshlrev_b32_e32 v92, 16, v106
	v_and_b32_e32 v93, 0xffff0000, v106
	v_lshlrev_b32_e32 v94, 16, v234
	v_and_b32_e32 v95, 0xffff0000, v234
	v_mul_f32_e32 v92, v92, v94
	v_mul_f32_e32 v93, v93, v95
	v_cvt_pk_bf16_f32 v122, v92, v93
	v_lshlrev_b32_e32 v92, 16, v107
	v_and_b32_e32 v93, 0xffff0000, v107
	v_lshlrev_b32_e32 v94, 16, v235
	v_and_b32_e32 v95, 0xffff0000, v235
	v_mul_f32_e32 v92, v92, v94
	v_mul_f32_e32 v93, v93, v95
	v_cvt_pk_bf16_f32 v123, v92, v93
	global_store_dwordx4 v[244:245], v[120:123], off
	s_waitcnt lgkmcnt(0)
	v_lshlrev_b32_e32 v92, 16, v108
	v_and_b32_e32 v93, 0xffff0000, v108
	v_lshlrev_b32_e32 v94, 16, v236
	v_and_b32_e32 v95, 0xffff0000, v236
	v_mul_f32_e32 v92, v92, v94
	v_mul_f32_e32 v93, v93, v95
	v_cvt_pk_bf16_f32 v124, v92, v93
	v_lshlrev_b32_e32 v92, 16, v109
	v_and_b32_e32 v93, 0xffff0000, v109
	v_lshlrev_b32_e32 v94, 16, v237
	v_and_b32_e32 v95, 0xffff0000, v237
	v_mul_f32_e32 v92, v92, v94
	v_mul_f32_e32 v93, v93, v95
	v_cvt_pk_bf16_f32 v125, v92, v93
	v_lshlrev_b32_e32 v92, 16, v110
	v_and_b32_e32 v93, 0xffff0000, v110
	v_lshlrev_b32_e32 v94, 16, v238
	v_and_b32_e32 v95, 0xffff0000, v238
	v_mul_f32_e32 v92, v92, v94
	v_mul_f32_e32 v93, v93, v95
	v_cvt_pk_bf16_f32 v126, v92, v93
	v_lshlrev_b32_e32 v92, 16, v111
	v_and_b32_e32 v93, 0xffff0000, v111
	v_lshlrev_b32_e32 v94, 16, v239
	v_and_b32_e32 v95, 0xffff0000, v239
	v_mul_f32_e32 v92, v92, v94
	v_mul_f32_e32 v93, v93, v95
	v_cvt_pk_bf16_f32 v127, v92, v93
	global_store_dwordx4 v[222:223], v[124:127], off
	s_branch .LBB0_829
.Lepi_m1:
	s_add_i32 s37, s21, 16
	v_add_u32_e32 v82, s37, v150
	v_mov_b32_e32 v83, 0
	s_lshl_b32 s30, s24, 1
	s_mov_b32 s31, 0
	s_mov_b64 s[34:35], 0x2000
	s_mov_b64 s[38:39], 0x4000
	global_load_dwordx4 v[184:187], v[132:133], off offset:256
	global_load_dwordx4 v[188:191], v[132:133], off offset:288
	global_load_dwordx4 v[192:195], v[132:133], off offset:320
	global_load_dwordx4 v[196:199], v[132:133], off offset:352
	global_load_dwordx4 v[200:203], v[132:133], off offset:384
	global_load_dwordx4 v[204:207], v[132:133], off offset:416
	global_load_dwordx4 v[208:211], v[132:133], off offset:448
	global_load_dwordx4 v[212:215], v[132:133], off offset:480
	v_lshlrev_b64 v[92:93], 11, v[82:83]
	v_lshlrev_b64 v[94:95], 12, v[82:83]
	v_lshl_add_u64 v[92:93], v[92:93], 0, s[30:31]
	v_lshl_add_u64 v[94:95], v[94:95], 0, s[30:31]
	v_lshl_add_u64 v[140:141], v[134:135], 0, v[92:93]
	v_lshl_add_u64 v[240:241], v[138:139], 0, v[94:95]
	v_lshl_add_u64 v[142:143], v[140:141], 0, s[34:35]
	v_lshl_add_u64 v[242:243], v[240:241], 0, s[38:39]
	v_lshl_add_u64 v[144:145], v[142:143], 0, s[34:35]
	v_lshl_add_u64 v[244:245], v[242:243], 0, s[38:39]
	v_lshl_add_u64 v[146:147], v[144:145], 0, s[34:35]
	v_lshl_add_u64 v[222:223], v[244:245], 0, s[38:39]
	global_load_dwordx4 v[224:227], v[140:141], off
	global_load_dwordx4 v[228:231], v[142:143], off
	global_load_dwordx4 v[232:235], v[144:145], off
	global_load_dwordx4 v[236:239], v[146:147], off
; __device__ __forceinline__ void attn_unit(unsigned char* ws, const float* sub_g, LAS unsigned char* lds, int h, int qb, float negM, float lam) {
;     ...
;     if (map == 1) {
;         const float f = inv * lam;
; #pragma unroll
;         for (int b = 0; b < 4; ++b)
; #pragma unroll
;             for (int r = 0; r < 16; ++r) xw[(b * 16 + r) * 64 + lane] = o[b][r] * f;
;     }
;     __syncthreads();
;     if (map == 0) {
;         float ss = 0.f;
; #pragma unroll
;         for (int b = 0; b < 4; ++b)
; #pragma unroll
;             for (int r = 0; r < 16; ++r) { const float v = o[b][r] * inv - xw[(b * 16 + r) * 64 + lane]; o[b][r] = v; ss += v * v; }
;         ss += __shfl_xor(ss, 32);
	v_mul_f32_e32 v91, v129, v90
	v_mul_f32_e32 v92, v64, v91
	v_mul_f32_e32 v93, v65, v91
	ds_write2st64_b32 v80, v92, v93 offset0:32 offset1:33
	v_mul_f32_e32 v94, v66, v91
	v_mul_f32_e32 v95, v67, v91
	ds_write2st64_b32 v80, v94, v95 offset0:34 offset1:35
	v_mul_f32_e32 v92, v68, v91
	v_mul_f32_e32 v93, v69, v91
	ds_write2st64_b32 v80, v92, v93 offset0:36 offset1:37
	v_mul_f32_e32 v94, v70, v91
	v_mul_f32_e32 v95, v71, v91
	ds_write2st64_b32 v80, v94, v95 offset0:38 offset1:39
	v_mul_f32_e32 v92, v72, v91
	v_mul_f32_e32 v93, v73, v91
	ds_write2st64_b32 v80, v92, v93 offset0:40 offset1:41
	v_mul_f32_e32 v94, v74, v91
	v_mul_f32_e32 v95, v75, v91
	ds_write2st64_b32 v80, v94, v95 offset0:42 offset1:43
	v_mul_f32_e32 v92, v76, v91
	v_mul_f32_e32 v93, v77, v91
	ds_write2st64_b32 v80, v92, v93 offset0:44 offset1:45
	v_mul_f32_e32 v94, v78, v91
	v_mul_f32_e32 v95, v79, v91
	ds_write2st64_b32 v80, v94, v95 offset0:46 offset1:47
	v_mul_f32_e32 v92, v48, v91
	v_mul_f32_e32 v93, v49, v91
	ds_write2st64_b32 v80, v92, v93 offset0:48 offset1:49
	v_mul_f32_e32 v94, v50, v91
	v_mul_f32_e32 v95, v51, v91
	ds_write2st64_b32 v80, v94, v95 offset0:50 offset1:51
	v_mul_f32_e32 v92, v52, v91
	v_mul_f32_e32 v93, v53, v91
	ds_write2st64_b32 v80, v92, v93 offset0:52 offset1:53
	v_mul_f32_e32 v94, v54, v91
	v_mul_f32_e32 v95, v55, v91
	ds_write2st64_b32 v80, v94, v95 offset0:54 offset1:55
	v_mul_f32_e32 v92, v56, v91
	v_mul_f32_e32 v93, v57, v91
	ds_write2st64_b32 v80, v92, v93 offset0:56 offset1:57
	v_mul_f32_e32 v94, v58, v91
	v_mul_f32_e32 v95, v59, v91
	ds_write2st64_b32 v80, v94, v95 offset0:58 offset1:59
	v_mul_f32_e32 v92, v60, v91
	v_mul_f32_e32 v93, v61, v91
	ds_write2st64_b32 v80, v92, v93 offset0:60 offset1:61
	v_mul_f32_e32 v94, v62, v91
	v_mul_f32_e32 v95, v63, v91
	ds_write2st64_b32 v80, v94, v95 offset0:62 offset1:63
	v_lshl_add_u32 v81, v149, 3, v155
	v_add_u32_e32 v81, s29, v81
	v_lshl_add_u32 v84, v153, 4, v137
	v_add_u32_e32 v84, s29, v84
	s_lshr_b32 s36, s29, 5
	s_add_i32 s36, s36, 0x20000
	v_lshl_add_u32 v85, v148, 2, s36
	s_waitcnt lgkmcnt(0)
	s_barrier
	ds_read2st64_b32 v[96:97], v80 offset0:0 offset1:1
	ds_read2st64_b32 v[98:99], v80 offset0:2 offset1:3
	ds_read2st64_b32 v[100:101], v80 offset0:4 offset1:5
	ds_read2st64_b32 v[102:103], v80 offset0:6 offset1:7
	ds_read2st64_b32 v[104:105], v80 offset0:8 offset1:9
	ds_read2st64_b32 v[106:107], v80 offset0:10 offset1:11
	ds_read2st64_b32 v[108:109], v80 offset0:12 offset1:13
	ds_read2st64_b32 v[110:111], v80 offset0:14 offset1:15
	s_waitcnt lgkmcnt(7)
	v_fma_f32 v32, -v32, v91, v96
	v_mul_f32_e32 v86, v32, v32
	v_fma_f32 v33, -v33, v91, v97
	v_mul_f32_e32 v87, v33, v33
	s_waitcnt lgkmcnt(6)
	v_fma_f32 v34, -v34, v91, v98
	v_fmac_f32_e32 v86, v34, v34
	v_fma_f32 v35, -v35, v91, v99
	v_fmac_f32_e32 v87, v35, v35
	s_waitcnt lgkmcnt(5)
	v_fma_f32 v36, -v36, v91, v100
	v_fmac_f32_e32 v86, v36, v36
	v_fma_f32 v37, -v37, v91, v101
	v_fmac_f32_e32 v87, v37, v37
	s_waitcnt lgkmcnt(4)
	v_fma_f32 v38, -v38, v91, v102
	v_fmac_f32_e32 v86, v38, v38
	v_fma_f32 v39, -v39, v91, v103
	v_fmac_f32_e32 v87, v39, v39
	ds_read2st64_b32 v[112:113], v80 offset0:16 offset1:17
	ds_read2st64_b32 v[114:115], v80 offset0:18 offset1:19
	ds_read2st64_b32 v[116:117], v80 offset0:20 offset1:21
	ds_read2st64_b32 v[118:119], v80 offset0:22 offset1:23
	ds_read2st64_b32 v[120:121], v80 offset0:24 offset1:25
	ds_read2st64_b32 v[122:123], v80 offset0:26 offset1:27
	ds_read2st64_b32 v[124:125], v80 offset0:28 offset1:29
	ds_read2st64_b32 v[126:127], v80 offset0:30 offset1:31
	s_waitcnt lgkmcnt(11)
	v_fma_f32 v40, -v40, v91, v104
	v_fmac_f32_e32 v86, v40, v40
	v_fma_f32 v41, -v41, v91, v105
	v_fmac_f32_e32 v87, v41, v41
	s_waitcnt lgkmcnt(10)
	v_fma_f32 v42, -v42, v91, v106
	v_fmac_f32_e32 v86, v42, v42
	v_fma_f32 v43, -v43, v91, v107
	v_fmac_f32_e32 v87, v43, v43
	s_waitcnt lgkmcnt(9)
	v_fma_f32 v44, -v44, v91, v108
	v_fmac_f32_e32 v86, v44, v44
	v_fma_f32 v45, -v45, v91, v109
	v_fmac_f32_e32 v87, v45, v45
	s_waitcnt lgkmcnt(8)
	v_fma_f32 v46, -v46, v91, v110
	v_fmac_f32_e32 v86, v46, v46
	v_fma_f32 v47, -v47, v91, v111
	v_fmac_f32_e32 v87, v47, v47
	s_waitcnt lgkmcnt(7)
	v_fma_f32 v16, -v16, v91, v112
	v_fmac_f32_e32 v86, v16, v16
	v_fma_f32 v17, -v17, v91, v113
	v_fmac_f32_e32 v87, v17, v17
	s_waitcnt lgkmcnt(6)
	v_fma_f32 v18, -v18, v91, v114
	v_fmac_f32_e32 v86, v18, v18
	v_fma_f32 v19, -v19, v91, v115
	v_fmac_f32_e32 v87, v19, v19
	s_waitcnt lgkmcnt(5)
	v_fma_f32 v20, -v20, v91, v116
	v_fmac_f32_e32 v86, v20, v20
	v_fma_f32 v21, -v21, v91, v117
	v_fmac_f32_e32 v87, v21, v21
	s_waitcnt lgkmcnt(4)
	v_fma_f32 v22, -v22, v91, v118
	v_fmac_f32_e32 v86, v22, v22
	v_fma_f32 v23, -v23, v91, v119
	v_fmac_f32_e32 v87, v23, v23
	s_waitcnt lgkmcnt(3)
	v_fma_f32 v24, -v24, v91, v120
	v_fmac_f32_e32 v86, v24, v24
	v_fma_f32 v25, -v25, v91, v121
	v_fmac_f32_e32 v87, v25, v25
	s_waitcnt lgkmcnt(2)
	v_fma_f32 v26, -v26, v91, v122
	v_fmac_f32_e32 v86, v26, v26
	v_fma_f32 v27, -v27, v91, v123
	v_fmac_f32_e32 v87, v27, v27
	s_waitcnt lgkmcnt(1)
	v_fma_f32 v28, -v28, v91, v124
	v_fmac_f32_e32 v86, v28, v28
	v_fma_f32 v29, -v29, v91, v125
	v_fmac_f32_e32 v87, v29, v29
	s_waitcnt lgkmcnt(0)
	v_fma_f32 v30, -v30, v91, v126
	v_fmac_f32_e32 v86, v30, v30
	v_fma_f32 v31, -v31, v91, v127
	v_fmac_f32_e32 v87, v31, v31
	v_add_f32_e32 v86, v86, v87
	v_mov_b32_e32 v92, v86
	s_nop 1
	v_permlane32_swap_b32_e32 v92, v86
	v_add_f32_e32 v86, v86, v92
	ds_write_b32 v85, v86 offset:256
	s_waitcnt lgkmcnt(0)
	s_barrier
; #define LAS __attribute__((address_space(3)))
; __device__ __forceinline__ unsigned cvtpk(float lo, float hi) { f32x2 v = {lo, hi}; bf16x2_t b = __builtin_convertvector(v, bf16x2_t); return __builtin_bit_cast(unsigned, b); }
; __device__ __forceinline__ void attn_unit(unsigned char* ws, const float* sub_g, LAS unsigned char* lds, int h, int qb, float negM, float lam) {
;     ...
;         ss += __shfl_xor(ss, 32);
;         const float rs = __builtin_amdgcn_rsqf(ss * (1.0f / VD) + EPS) * (1.0f - LAM_INIT);
;         LAS unsigned char* stg = (LAS unsigned char*)xw;
; #pragma unroll
;         for (int b = 0; b < 4; ++b)
; #pragma unroll
;             for (int r4 = 0; r4 < 4; ++r4) {
;                 const int dv = 32 * b + 8 * r4 + 4 * hi;
;                 const f32x4 sg = *(const f32x4*)(sub_g + dv);
;                 u32x2 w; w.x = cvtpk(o[b][4 * r4 + 0] * rs * sg[0], o[b][4 * r4 + 1] * rs * sg[1]); w.y = cvtpk(o[b][4 * r4 + 2] * rs * sg[2], o[b][4 * r4 + 3] * rs * sg[3]);
;                 *(LAS u32x2*)(stg + r32 * 272 + dv * 2) = w;
;             }
;         asm volatile("s_waitcnt lgkmcnt(0)" ::: "memory");
	ds_read_b32 v92, v85
	s_waitcnt lgkmcnt(0)
	v_add_f32_e32 v86, v86, v92
	v_fmamk_f32 v86, v86, 0x3c000000, v182
	v_rsq_f32_e32 v86, v86
	s_nop 0
	v_mul_f32_e32 v86, 0x3f4ccccd, v86
	s_waitcnt vmcnt(4)
	v_mul_f32_e32 v32, v32, v86
	v_mul_f32_e32 v33, v33, v86
	v_mul_f32_e32 v34, v34, v86
	v_mul_f32_e32 v35, v35, v86
	v_mul_f32_e32 v32, v32, v184
	v_mul_f32_e32 v33, v33, v185
	v_mul_f32_e32 v34, v34, v186
	v_mul_f32_e32 v35, v35, v187
	v_cvt_pk_bf16_f32 v92, v32, v33
	v_cvt_pk_bf16_f32 v93, v34, v35
	ds_write_b64 v81, v[92:93] offset:128
	v_mul_f32_e32 v36, v36, v86
	v_mul_f32_e32 v37, v37, v86
	v_mul_f32_e32 v38, v38, v86
	v_mul_f32_e32 v39, v39, v86
	v_mul_f32_e32 v36, v36, v188
	v_mul_f32_e32 v37, v37, v189
	v_mul_f32_e32 v38, v38, v190
	v_mul_f32_e32 v39, v39, v191
	v_cvt_pk_bf16_f32 v94, v36, v37
	v_cvt_pk_bf16_f32 v95, v38, v39
	ds_write_b64 v81, v[94:95] offset:144
	v_mul_f32_e32 v40, v40, v86
	v_mul_f32_e32 v41, v41, v86
	v_mul_f32_e32 v42, v42, v86
	v_mul_f32_e32 v43, v43, v86
	v_mul_f32_e32 v40, v40, v192
	v_mul_f32_e32 v41, v41, v193
	v_mul_f32_e32 v42, v42, v194
	v_mul_f32_e32 v43, v43, v195
	v_cvt_pk_bf16_f32 v92, v40, v41
	v_cvt_pk_bf16_f32 v93, v42, v43
	ds_write_b64 v81, v[92:93] offset:160
	v_mul_f32_e32 v44, v44, v86
	v_mul_f32_e32 v45, v45, v86
	v_mul_f32_e32 v46, v46, v86
	v_mul_f32_e32 v47, v47, v86
	v_mul_f32_e32 v44, v44, v196
	v_mul_f32_e32 v45, v45, v197
	v_mul_f32_e32 v46, v46, v198
	v_mul_f32_e32 v47, v47, v199
	v_cvt_pk_bf16_f32 v94, v44, v45
	v_cvt_pk_bf16_f32 v95, v46, v47
	ds_write_b64 v81, v[94:95] offset:176
	v_mul_f32_e32 v16, v16, v86
	v_mul_f32_e32 v17, v17, v86
	v_mul_f32_e32 v18, v18, v86
	v_mul_f32_e32 v19, v19, v86
	v_mul_f32_e32 v16, v16, v200
	v_mul_f32_e32 v17, v17, v201
	v_mul_f32_e32 v18, v18, v202
	v_mul_f32_e32 v19, v19, v203
	v_cvt_pk_bf16_f32 v92, v16, v17
	v_cvt_pk_bf16_f32 v93, v18, v19
	ds_write_b64 v81, v[92:93] offset:192
	v_mul_f32_e32 v20, v20, v86
	v_mul_f32_e32 v21, v21, v86
	v_mul_f32_e32 v22, v22, v86
	v_mul_f32_e32 v23, v23, v86
	v_mul_f32_e32 v20, v20, v204
	v_mul_f32_e32 v21, v21, v205
	v_mul_f32_e32 v22, v22, v206
	v_mul_f32_e32 v23, v23, v207
	v_cvt_pk_bf16_f32 v94, v20, v21
	v_cvt_pk_bf16_f32 v95, v22, v23
	ds_write_b64 v81, v[94:95] offset:208
	v_mul_f32_e32 v24, v24, v86
	v_mul_f32_e32 v25, v25, v86
	v_mul_f32_e32 v26, v26, v86
	v_mul_f32_e32 v27, v27, v86
	v_mul_f32_e32 v24, v24, v208
	v_mul_f32_e32 v25, v25, v209
	v_mul_f32_e32 v26, v26, v210
	v_mul_f32_e32 v27, v27, v211
	v_cvt_pk_bf16_f32 v92, v24, v25
	v_cvt_pk_bf16_f32 v93, v26, v27
	ds_write_b64 v81, v[92:93] offset:224
	v_mul_f32_e32 v28, v28, v86
	v_mul_f32_e32 v29, v29, v86
	v_mul_f32_e32 v30, v30, v86
	v_mul_f32_e32 v31, v31, v86
	v_mul_f32_e32 v28, v28, v212
	v_mul_f32_e32 v29, v29, v213
	v_mul_f32_e32 v30, v30, v214
	v_mul_f32_e32 v31, v31, v215
	v_cvt_pk_bf16_f32 v94, v28, v29
	v_cvt_pk_bf16_f32 v95, v30, v31
	ds_write_b64 v81, v[94:95] offset:240
	s_waitcnt lgkmcnt(0)
	s_barrier
; #define LAS __attribute__((address_space(3)))
; __device__ __forceinline__ unsigned cvtpk(float lo, float hi) { f32x2 v = {lo, hi}; bf16x2_t b = __builtin_convertvector(v, bf16x2_t); return __builtin_bit_cast(unsigned, b); }
; __device__ __forceinline__ void attn_unit(unsigned char* ws, const float* sub_g, LAS unsigned char* lds, int h, int qb, float negM, float lam) {
;     ...
; #pragma unroll
;         for (int i = 0; i < 8; ++i) {
;             const int q = (lane >> 4) + 4 * i, ch = lane & 15;
;             const u32x4 ov = *(const LAS u32x4*)(stg + q * 272 + ch * 16);
;             const size_t tok = (size_t)(qrow0 + q);
;             const u32x4 gv = gvs[i];
;             u32x4 w;
;             w.x = cvtpk(bf_lo(ov.x) * bf_lo(gv.x), bf_hi(ov.x) * bf_hi(gv.x)); w.y = cvtpk(bf_lo(ov.y) * bf_lo(gv.y), bf_hi(ov.y) * bf_hi(gv.y));
;             w.z = cvtpk(bf_lo(ov.z) * bf_lo(gv.z), bf_hi(ov.z) * bf_hi(gv.z)); w.w = cvtpk(bf_lo(ov.w) * bf_lo(gv.w), bf_hi(ov.w) * bf_hi(gv.w));
;             *(u32x4*)(MIX + tok * DM + h * 128 + ch * 8) = w;
;         }
	ds_read_b128 v[96:99], v84 offset:4352
	ds_read_b128 v[100:103], v84 offset:5440
	ds_read_b128 v[104:107], v84 offset:6528
	ds_read_b128 v[108:111], v84 offset:7616
	s_waitcnt vmcnt(0)
	s_waitcnt lgkmcnt(3)
	v_lshlrev_b32_e32 v92, 16, v96
	v_and_b32_e32 v93, 0xffff0000, v96
	v_lshlrev_b32_e32 v94, 16, v224
	v_and_b32_e32 v95, 0xffff0000, v224
	v_mul_f32_e32 v92, v92, v94
	v_mul_f32_e32 v93, v93, v95
	v_cvt_pk_bf16_f32 v112, v92, v93
	v_lshlrev_b32_e32 v92, 16, v97
	v_and_b32_e32 v93, 0xffff0000, v97
	v_lshlrev_b32_e32 v94, 16, v225
	v_and_b32_e32 v95, 0xffff0000, v225
	v_mul_f32_e32 v92, v92, v94
	v_mul_f32_e32 v93, v93, v95
	v_cvt_pk_bf16_f32 v113, v92, v93
	v_lshlrev_b32_e32 v92, 16, v98
	v_and_b32_e32 v93, 0xffff0000, v98
	v_lshlrev_b32_e32 v94, 16, v226
	v_and_b32_e32 v95, 0xffff0000, v226
	v_mul_f32_e32 v92, v92, v94
	v_mul_f32_e32 v93, v93, v95
	v_cvt_pk_bf16_f32 v114, v92, v93
	v_lshlrev_b32_e32 v92, 16, v99
	v_and_b32_e32 v93, 0xffff0000, v99
	v_lshlrev_b32_e32 v94, 16, v227
	v_and_b32_e32 v95, 0xffff0000, v227
	v_mul_f32_e32 v92, v92, v94
	v_mul_f32_e32 v93, v93, v95
	v_cvt_pk_bf16_f32 v115, v92, v93
	global_store_dwordx4 v[240:241], v[112:115], off
	s_waitcnt lgkmcnt(2)
	v_lshlrev_b32_e32 v92, 16, v100
	v_and_b32_e32 v93, 0xffff0000, v100
	v_lshlrev_b32_e32 v94, 16, v228
	v_and_b32_e32 v95, 0xffff0000, v228
	v_mul_f32_e32 v92, v92, v94
	v_mul_f32_e32 v93, v93, v95
	v_cvt_pk_bf16_f32 v116, v92, v93
	v_lshlrev_b32_e32 v92, 16, v101
	v_and_b32_e32 v93, 0xffff0000, v101
	v_lshlrev_b32_e32 v94, 16, v229
	v_and_b32_e32 v95, 0xffff0000, v229
	v_mul_f32_e32 v92, v92, v94
	v_mul_f32_e32 v93, v93, v95
	v_cvt_pk_bf16_f32 v117, v92, v93
	v_lshlrev_b32_e32 v92, 16, v102
	v_and_b32_e32 v93, 0xffff0000, v102
	v_lshlrev_b32_e32 v94, 16, v230
	v_and_b32_e32 v95, 0xffff0000, v230
	v_mul_f32_e32 v92, v92, v94
	v_mul_f32_e32 v93, v93, v95
	v_cvt_pk_bf16_f32 v118, v92, v93
	v_lshlrev_b32_e32 v92, 16, v103
	v_and_b32_e32 v93, 0xffff0000, v103
	v_lshlrev_b32_e32 v94, 16, v231
	v_and_b32_e32 v95, 0xffff0000, v231
	v_mul_f32_e32 v92, v92, v94
	v_mul_f32_e32 v93, v93, v95
	v_cvt_pk_bf16_f32 v119, v92, v93
	global_store_dwordx4 v[242:243], v[116:119], off
	s_waitcnt lgkmcnt(1)
	v_lshlrev_b32_e32 v92, 16, v104
	v_and_b32_e32 v93, 0xffff0000, v104
	v_lshlrev_b32_e32 v94, 16, v232
	v_and_b32_e32 v95, 0xffff0000, v232
	v_mul_f32_e32 v92, v92, v94
	v_mul_f32_e32 v93, v93, v95
	v_cvt_pk_bf16_f32 v120, v92, v93
	v_lshlrev_b32_e32 v92, 16, v105
	v_and_b32_e32 v93, 0xffff0000, v105
	v_lshlrev_b32_e32 v94, 16, v233
	v_and_b32_e32 v95, 0xffff0000, v233
	v_mul_f32_e32 v92, v92, v94
	v_mul_f32_e32 v93, v93, v95
	v_cvt_pk_bf16_f32 v121, v92, v93
	v_lshlrev_b32_e32 v92, 16, v106
	v_and_b32_e32 v93, 0xffff0000, v106
	v_lshlrev_b32_e32 v94, 16, v234
	v_and_b32_e32 v95, 0xffff0000, v234
	v_mul_f32_e32 v92, v92, v94
	v_mul_f32_e32 v93, v93, v95
	v_cvt_pk_bf16_f32 v122, v92, v93
	v_lshlrev_b32_e32 v92, 16, v107
	v_and_b32_e32 v93, 0xffff0000, v107
	v_lshlrev_b32_e32 v94, 16, v235
	v_and_b32_e32 v95, 0xffff0000, v235
	v_mul_f32_e32 v92, v92, v94
	v_mul_f32_e32 v93, v93, v95
	v_cvt_pk_bf16_f32 v123, v92, v93
	global_store_dwordx4 v[244:245], v[120:123], off
	s_waitcnt lgkmcnt(0)
	v_lshlrev_b32_e32 v92, 16, v108
	v_and_b32_e32 v93, 0xffff0000, v108
	v_lshlrev_b32_e32 v94, 16, v236
	v_and_b32_e32 v95, 0xffff0000, v236
	v_mul_f32_e32 v92, v92, v94
	v_mul_f32_e32 v93, v93, v95
	v_cvt_pk_bf16_f32 v124, v92, v93
	v_lshlrev_b32_e32 v92, 16, v109
	v_and_b32_e32 v93, 0xffff0000, v109
	v_lshlrev_b32_e32 v94, 16, v237
	v_and_b32_e32 v95, 0xffff0000, v237
	v_mul_f32_e32 v92, v92, v94
	v_mul_f32_e32 v93, v93, v95
	v_cvt_pk_bf16_f32 v125, v92, v93
	v_lshlrev_b32_e32 v92, 16, v110
	v_and_b32_e32 v93, 0xffff0000, v110
	v_lshlrev_b32_e32 v94, 16, v238
	v_and_b32_e32 v95, 0xffff0000, v238
	v_mul_f32_e32 v92, v92, v94
	v_mul_f32_e32 v93, v93, v95
	v_cvt_pk_bf16_f32 v126, v92, v93
	v_lshlrev_b32_e32 v92, 16, v111
	v_and_b32_e32 v93, 0xffff0000, v111
	v_lshlrev_b32_e32 v94, 16, v239
	v_and_b32_e32 v95, 0xffff0000, v239
	v_mul_f32_e32 v92, v92, v94
	v_mul_f32_e32 v93, v93, v95
	v_cvt_pk_bf16_f32 v127, v92, v93
	global_store_dwordx4 v[222:223], v[124:127], off
	s_branch .LBB0_829
